# diff-attn tile loop: 2 barriers per tile, wave halves offset by one barrier (MFMA vs softmax overlap)
# baseline (speedup 1.0000x reference)
; #define WAIT_TILE(all_) do { if (all_) asm volatile("s_waitcnt vmcnt(0) lgkmcnt(0)" ::: "memory"); \
;         else if constexpr (MODE == 0) asm volatile("s_waitcnt vmcnt(5) lgkmcnt(0)" ::: "memory"); else asm volatile("s_waitcnt vmcnt(4) lgkmcnt(0)" ::: "memory"); \
;         __builtin_amdgcn_s_barrier(); asm volatile("" ::: "memory"); } while (0)
; template <int MODE>
; __device__ __forceinline__ void attn_unit(LAS char* lds, const AttnPtrs& A, int b, int qb) {
;     ...
;     const int tid = opaque_tid(), lane = tid & 63, r32 = lane & 31, hi = lane >> 5, wid = __builtin_amdgcn_readfirstlane(tid >> 6);
;     const int strm = (MODE == 2) ? (wid & 1) : 0;
;     const size_t rowbase = (size_t)b * SEQ; const int q0 = (MODE == 2) ? qb * 128 + (wid >> 1) * 32 : qb * 256 + wid * 32; const int cw = q0 >> 6, NT = (MODE == 2) ? 2 * qb + 2 : 4 * qb + 4;
;     const size_t qrow = rowbase + q0 + r32;
;     const bf16_t* ksrc[2]; const bf16_t* vsrc[2];
; #pragma unroll
;     for (int i = 0; i < 2; ++i) { const unsigned row = 4u * (2 * wid + i) + (lane >> 4), ch = (lane & 15) ^ (((row & 3) << 2) | ((row >> 2) & 3));
;         ksrc[i] = A.K + (rowbase + row) * A.ldk + ch * 8; vsrc[i] = A.V + (rowbase + row) * A.ldv + ch * 8; }
;     const bf16_t* k64src = nullptr;
;     if constexpr (MODE == 0) { const unsigned row = 8u * wid + (lane >> 3), ch = (lane & 7) ^ ((row >> 1) & 7); k64src = A.K64 + (rowbase + row) * 64 + ch * 8; }
;     const unsigned fK = ((r32 & 3) << 2) | ((r32 >> 2) & 3);
;     const unsigned g64 = (r32 >> 1) & 7;
;     const int q4 = (lane & 15) >> 2, p4 = lane & 3, blk = (lane >> 4) & 1;
;     unsigned vrow[2], vlow[2];
; #pragma unroll
;     for (int t = 0; t < 2; ++t) { vrow[t] = 4 * hi + 8 * t + q4; vlow[t] = (unsigned)((2 * blk + (p4 >> 1)) ^ ((hi + 2 * t) & 3)); }
;     ...
;     STAGE(0, 0); STAGE(1, 1);
;     bf16x8 qf[NQ];
; #pragma unroll
;     for (int s = 0; s < NQ; ++s) qf[s] = *(const bf16x8*)(A.Q + qrow * A.ldq + 64 * strm + 16 * s + 8 * hi);
;     ...
;     WAIT_TILE(true);
.LBB0_623:
	s_mul_hi_i32 s3, s2, 0x99999999
	s_lshr_b32 s4, s3, 31
	s_ashr_i32 s3, s3, 3
	s_add_i32 s3, s3, s4
	s_mul_hi_i32 s4, s2, 0x66666667
	s_lshr_b32 s5, s4, 31
	s_lshr_b32 s4, s4, 3
	s_add_i32 s4, s4, s5
	s_mul_i32 s4, s4, 20
	s_sub_i32 s4, s2, s4
	s_bfe_i32 s2, s4, 0x80000
	s_mulk_i32 s2, 0x67
	s_sext_i32_i16 s5, s2
	s_ashr_i32 s5, s5, 9
	s_bfe_u32 s2, s2, 0x1000f
	s_add_i32 s2, s5, s2
	s_mul_i32 s5, s2, 5
	s_sub_i32 s4, s4, s5
	s_sext_i32_i8 s4, s4
	s_lshl_b32 s4, s4, 7
	s_ashr_i32 s5, s4, 31
	s_add_i32 s24, s3, 31
	s_lshl_b64 s[4:5], s[4:5], 1
	s_add_u32 s6, s10, s4
	s_addc_u32 s7, s11, s5
	s_add_u32 s28, s12, s4
	s_addc_u32 s29, s13, s5
	s_add_u32 s34, s18, s4
	s_getreg_b32 s8, hwreg(HW_REG_HW_ID, 0, 6)
	s_addc_u32 s35, s19, s5
	s_lshl_b32 s8, s8, 2
	s_and_b32 s8, s8, 0xfc
	s_add_i32 s8, s8, 0x20040
	v_mov_b32_e32 v0, s8
	ds_read_b32 v0, v0
	s_lshl_b32 s25, s24, 7
	v_mov_b64_e32 v[8:9], s[28:29]
	v_mov_b64_e32 v[12:13], s[34:35]
	s_lshl_b32 s24, s24, 1
	s_waitcnt lgkmcnt(0)
	v_readfirstlane_b32 s8, v0
	v_mov_b32_e32 v0, v1
	v_mov_b32_e32 v3, v1
	v_mbcnt_lo_u32_b32 v0, -1, v0
	v_mbcnt_hi_u32_b32 v6, -1, v0
	v_lshl_or_b32 v0, s8, 6, v6
	s_bfe_i64 s[8:9], s[2:3], 0x100000
	v_readfirstlane_b32 s23, v0
	s_ashr_i32 s26, s23, 6
	s_ashr_i32 s23, s23, 7
	s_lshl_b32 s27, s23, 5
	s_add_i32 s27, s27, s25
	s_lshl_b32 s25, s26, 3
	v_bfe_u32 v16, v6, 4, 2
	s_lshl_b64 s[8:9], s[8:9], 12
	v_or_b32_e32 v0, s25, v16
	v_lshl_add_u64 v[4:5], s[8:9], 0, v[0:1]
	s_lshl_b32 s44, s26, 1
	v_mad_u64_u32 v[10:11], s[28:29], v4, s84, v[8:9]
	v_mad_u64_u32 v[14:15], s[28:29], v4, s84, v[12:13]
	s_or_b32 s25, s25, 4
	v_and_b32_e32 v17, 15, v6
	v_lshlrev_b32_e32 v18, 2, v16
	s_and_b32 s44, s44, 2
	v_mad_i32_i24 v11, v5, s84, v11
	v_mad_i32_i24 v15, v5, s84, v15
	v_or_b32_e32 v4, s25, v16
	s_bfe_u32 s25, s25, 0x20002
	v_mov_b32_e32 v5, v1
	s_ashr_i32 s33, s27, 31
	v_bitop3_b32 v2, s44, v17, v18 bitop3:0x36
	v_bitop3_b32 v18, s25, v17, v18 bitop3:0x36
	v_lshl_add_u64 v[16:17], s[8:9], 0, v[4:5]
	s_ashr_i32 s25, s27, 6
	v_mad_u64_u32 v[8:9], s[28:29], v16, s84, v[8:9]
	v_mad_u64_u32 v[12:13], s[28:29], v16, s84, v[12:13]
	s_add_u32 s27, s8, s27
	s_addc_u32 s28, s9, s33
	s_lshl_b32 s9, s26, 11
	v_lshlrev_b32_e32 v2, 4, v2
	s_add_i32 s9, s9, 0
	v_lshl_add_u64 v[10:11], v[10:11], 0, v[2:3]
	v_mad_i32_i24 v9, v17, s84, v9
	v_lshlrev_b32_e32 v4, 4, v18
	s_mov_b32 m0, s9
	v_lshl_add_u64 v[8:9], v[8:9], 0, v[4:5]
	global_load_lds_dwordx4 v[10:11], off
	s_add_i32 m0, s9, 0x400
	v_lshl_add_u64 v[14:15], v[14:15], 0, v[2:3]
	v_mad_i32_i24 v13, v17, s84, v13
	global_load_lds_dwordx4 v[8:9], off
	s_add_i32 m0, s9, 0x4000
	v_lshl_add_u64 v[12:13], v[12:13], 0, v[4:5]
	global_load_lds_dwordx4 v[14:15], off
	s_add_i32 m0, s9, 0x4400
	v_lshl_add_u64 v[10:11], v[10:11], 0, s[60:61]
	global_load_lds_dwordx4 v[12:13], off
	s_add_i32 m0, s9, 0xa000
	v_lshl_add_u64 v[8:9], v[8:9], 0, s[60:61]
	global_load_lds_dwordx4 v[10:11], off
	s_add_i32 m0, s9, 0xa400
	v_and_b32_e32 v7, 31, v6
	global_load_lds_dwordx4 v[8:9], off
	v_lshl_add_u64 v[8:9], v[14:15], 0, s[60:61]
	s_add_i32 m0, s9, 0xe000
	v_or_b32_e32 v114, s27, v7
	global_load_lds_dwordx4 v[8:9], off
	v_lshl_add_u64 v[8:9], v[12:13], 0, s[60:61]
	s_add_i32 m0, s9, 0xe400
	s_and_b32 s8, s26, 1
	global_load_lds_dwordx4 v[8:9], off
	v_mov_b64_e32 v[8:9], s[6:7]
	v_mad_u64_u32 v[8:9], s[6:7], v114, s84, v[8:9]
	v_mov_b32_e32 v10, 0xa00
	v_bfe_u32 v16, v6, 5, 1
	v_mad_i32_i24 v9, s28, v10, v9
	s_lshl_b32 s68, s8, 7
	v_lshl_add_u64 v[8:9], v[8:9], 0, s[68:69]
	v_lshlrev_b32_e32 v10, 4, v16
	v_mov_b32_e32 v11, v1
	v_lshl_add_u64 v[8:9], v[8:9], 0, v[10:11]
	global_load_dwordx4 v[98:101], v[8:9], off
	global_load_dwordx4 v[102:105], v[8:9], off offset:32
	global_load_dwordx4 v[106:109], v[8:9], off offset:64
	global_load_dwordx4 v[110:113], v[8:9], off offset:96
	v_lshlrev_b32_e32 v17, 2, v6
	v_bfe_u32 v18, v6, 2, 2
	v_and_or_b32 v8, v17, 12, v18
	s_lshl_b32 s6, s8, 3
	v_lshlrev_b32_e32 v9, 3, v6
	v_mov_b32_e32 v10, 0x4000
	v_lshrrev_b32_e32 v19, 3, v6
	v_lshlrev_b32_e32 v124, 8, v7
	v_or_b32_e32 v7, s6, v16
	v_and_or_b32 v125, v9, 8, v10
	v_bitop3_b32 v9, s6, v8, v16 bitop3:0x36
	v_and_b32_e32 v19, 2, v19
	v_bfe_u32 v20, v6, 1, 1
	v_lshlrev_b32_e32 v126, 4, v9
	v_bitop3_b32 v9, v7, v8, 2 bitop3:0x36
	v_or_b32_e32 v21, v19, v20
	v_lshlrev_b32_e32 v127, 4, v9
	v_bitop3_b32 v9, v7, v8, 4 bitop3:0x36
	v_bitop3_b32 v7, v7, v8, 6 bitop3:0x36
	v_bitop3_b32 v19, v19, v16, v20 bitop3:0x36
	v_bitop3_b32 v23, v16, v21, 2 bitop3:0x36
	v_lshlrev_b32_e32 v129, 4, v7
	v_and_b32_e32 v7, 12, v6
	v_or_b32_e32 v8, v19, v7
	v_or_b32_e32 v7, v23, v7
	v_or_b32_e32 v20, 2, v16
	v_lshlrev_b32_e32 v133, 4, v7
	v_bitop3_b32 v7, v6, 4, 12 bitop3:0x6c
	v_lshlrev_b32_e32 v131, 4, v8
	v_bitop3_b32 v8, v21, v7, v16 bitop3:0xde
	v_bitop3_b32 v7, v20, v7, v21 bitop3:0xde
	v_lshlrev_b32_e32 v141, 4, v7
	v_bitop3_b32 v7, v6, 8, 12 bitop3:0x6c
	v_and_b32_e32 v123, 63, v6
	v_lshlrev_b32_e32 v140, 4, v8
	v_bitop3_b32 v8, v21, v7, v16 bitop3:0xde
	v_bitop3_b32 v7, v20, v7, v21 bitop3:0xde
	v_bitop3_b32 v6, v6, 12, v6 bitop3:0xc
	v_lshlrev_b32_e32 v143, 4, v7
	v_bitop3_b32 v7, v21, v6, v16 bitop3:0xde
	v_bitop3_b32 v6, v20, v6, v21 bitop3:0xde
	v_lshlrev_b32_e32 v145, 4, v6
	v_or_b32_e32 v6, 4, v0
	v_lshlrev_b32_e32 v144, 4, v7
	v_mad_u64_u32 v[6:7], s[6:7], v6, s84, 0
	s_sext_i32_i16 s2, s2
	v_mad_i64_i32 v[6:7], s[6:7], s2, v214, v[6:7]
	v_lshl_add_u64 v[4:5], v[6:7], 0, v[4:5]
	v_lshl_add_u64 v[116:117], s[14:15], 0, v[4:5]
	v_mad_u64_u32 v[4:5], s[6:7], v0, s84, 0
	v_lshlrev_b32_e32 v122, 2, v16
	v_mad_i64_i32 v[4:5], s[6:7], s2, v214, v[4:5]
	v_or_b32_e32 v22, v122, v18
	v_lshl_add_u64 v[2:3], v[4:5], 0, v[2:3]
	v_mov_b32_e32 v14, v1
	v_mov_b32_e32 v15, v1
	s_waitcnt vmcnt(0)
	s_waitcnt vmcnt(0) lgkmcnt(0)
	s_barrier
	s_cmp_lt_u32 s23, 2
	s_cbranch_scc1 .Lm2_noX
	s_barrier
; template <int MODE>
; __device__ __forceinline__ void attn_unit(LAS char* lds, const AttnPtrs& A, int b, int qb) {
;     ...
;     f32x16 o1[4];
; #pragma unroll
;     for (int c = 0; c < 4; ++c) o1[c] = f32x16{};
;     float m1 = -1e30f, l1 = 0.f;
;     unsigned long long mw_next = 0ull;
;     if constexpr (MODE == 1) { mw_next = A.MASK[qrow * 64]; asm volatile("" : "+v"(mw_next)); }
;     bf16x8 pk[4]; float a1 = 1.f;
;     ...
;     int st_cur = 0, st_nn = 2;
;     for (int t = 0; t < NT; ++t) {
;         unsigned mlo = 0, mhi = 0;
;         if constexpr (MODE == 1) { if (t <= cw) {
;             const unsigned long long w = mw_next; mlo = (unsigned)w >> (4 * hi); mhi = (unsigned)(w >> 32) >> (4 * hi);
;             asm volatile("" : "+v"(mlo), "+v"(mhi));
;             if (t < cw) { const unsigned long long* mp_ = A.MASK + qrow * 64 + t + 1; asm volatile("global_load_dwordx2 %0, %1, off" : "+v"(mw_next) : "v"(mp_) : "memory"); } } }
;         const bool more2 = (t + 2 < NT);
;         if (more2) STAGE(t + 2, st_nn);
.Lm2_noX:
	v_lshlrev_b32_e32 v128, 4, v9
	v_lshlrev_b32_e32 v130, 8, v22
	v_lshlrev_b32_e32 v142, 4, v8
	v_lshl_add_u64 v[118:119], s[14:15], 0, v[2:3]
	v_mov_b32_e32 v0, v1
	v_mov_b32_e32 v2, v1
	v_mov_b32_e32 v3, v1
	v_mov_b32_e32 v4, v1
	v_mov_b32_e32 v5, v1
	v_mov_b32_e32 v6, v1
	v_mov_b32_e32 v7, v1
	v_mov_b32_e32 v8, v1
	v_mov_b32_e32 v9, v1
	v_mov_b32_e32 v10, v1
	v_mov_b32_e32 v12, v1
	v_mov_b32_e32 v13, v1
	v_mov_b64_e32 v[64:65], v[14:15]
	v_mov_b64_e32 v[48:49], v[14:15]
	v_mov_b64_e32 v[32:33], v[14:15]
	s_lshl_b32 s6, s3, 1
	v_mov_b64_e32 v[62:63], v[12:13]
	v_mov_b64_e32 v[60:61], v[10:11]
	v_mov_b64_e32 v[58:59], v[8:9]
	v_mov_b64_e32 v[56:57], v[6:7]
	v_mov_b64_e32 v[54:55], v[4:5]
	v_mov_b64_e32 v[52:53], v[2:3]
	v_mov_b64_e32 v[50:51], v[0:1]
	v_mov_b64_e32 v[46:47], v[12:13]
	v_mov_b64_e32 v[44:45], v[10:11]
	v_mov_b64_e32 v[42:43], v[8:9]
	v_mov_b64_e32 v[40:41], v[6:7]
	v_mov_b64_e32 v[38:39], v[4:5]
	v_mov_b64_e32 v[36:37], v[2:3]
	v_mov_b64_e32 v[34:35], v[0:1]
	v_mov_b64_e32 v[30:31], v[12:13]
	v_mov_b64_e32 v[28:29], v[10:11]
	v_mov_b64_e32 v[26:27], v[8:9]
	v_mov_b64_e32 v[24:25], v[6:7]
	v_mov_b64_e32 v[22:23], v[4:5]
	v_mov_b64_e32 v[20:21], v[2:3]
	v_mov_b64_e32 v[18:19], v[0:1]
	v_mov_b64_e32 v[16:17], v[14:15]
	s_mov_b32 s16, 2
	s_mov_b32 s17, 0
	v_mov_b32_e32 v115, s28
	v_or_b32_e32 v132, 0x800, v130
	v_or_b32_e32 v134, 0x1000, v130
	v_or_b32_e32 v135, 0x1800, v130
	v_or_b32_e32 v136, 0x2000, v130
	v_or_b32_e32 v137, 0x2800, v130
	v_or_b32_e32 v138, 0x3000, v130
	v_or_b32_e32 v139, 0x3800, v130
	s_add_i32 s6, s6, 64
	v_mov_b32_e32 v148, 0xf149f2ca
	v_mov_b32_e32 v147, 0
	v_mov_b64_e32 v[14:15], v[12:13]
	v_mov_b64_e32 v[12:13], v[10:11]
	v_mov_b64_e32 v[10:11], v[8:9]
	v_mov_b64_e32 v[8:9], v[6:7]
	v_mov_b64_e32 v[6:7], v[4:5]
	v_mov_b64_e32 v[4:5], v[2:3]
	v_mov_b64_e32 v[2:3], v[0:1]
	s_mov_b32 s7, 0
	s_cmp_ge_u32 s7, s24
	s_cselect_b64 s[2:3], -1, 0
	s_and_b64 vcc, exec, s[2:3]
	s_cbranch_vccnz .LBB0_626
	s_branch .LBB0_625

; template <int MODE>
; __device__ __forceinline__ void attn_unit(LAS char* lds, const AttnPtrs& A, int b, int qb) {
;     ...
;         const bool more2 = (t + 2 < NT);
;         if (more2) STAGE(t + 2, st_nn);
;         if (t <= cw) {
;             const lptr sb = (lptr)(lds + st_cur * ST_BYTES);
;             f32x16 s0 = f32x16{}, s1 = f32x16{};
;             QK_PASS(NQ);
.LBB0_625:
	s_mul_i32 s26, s16, 0xa000
	v_lshl_add_u64 v[66:67], v[118:119], 0, s[4:5]
	s_add_i32 s26, s9, s26
	v_lshl_add_u64 v[68:69], v[66:67], 0, s[72:73]
	s_mov_b32 m0, s26
	v_lshl_add_u64 v[70:71], v[116:117], 0, s[4:5]
	global_load_lds_dwordx4 v[68:69], off
	v_lshl_add_u64 v[70:71], v[70:71], 0, s[72:73]
	s_add_i32 m0, s26, 0x400
	s_nop 0
	global_load_lds_dwordx4 v[70:71], off
.LBB0_626:
	s_cmp_gt_i32 s7, s25
	s_cbranch_scc1 .LBB0_630
	s_mul_i32 s26, s17, 0xa000
	s_add_i32 s26, s26, 0
	v_add_u32_e32 v0, s26, v124
	v_add_u32_e32 v70, v0, v126
	v_add_u32_e32 v74, v0, v127
	ds_read_b128 v[66:69], v70
	ds_read_b128 v[70:73], v70 offset:8192
	ds_read_b128 v[150:153], v74
	ds_read_b128 v[154:157], v74 offset:8192
	v_add_u32_e32 v74, v0, v128
	v_add_u32_e32 v0, v0, v129
	ds_read_b128 v[158:161], v74
	ds_read_b128 v[162:165], v74 offset:8192
	ds_read_b128 v[166:169], v0
	ds_read_b128 v[170:173], v0 offset:8192
	s_waitcnt lgkmcnt(0)
	v_mfma_f32_32x32x16_bf16 v[82:97], v[66:69], v[98:101], 0
	v_mfma_f32_32x32x16_bf16 v[66:81], v[70:73], v[98:101], 0
	v_mfma_f32_32x32x16_bf16 v[82:97], v[150:153], v[102:105], v[82:97]
	v_mfma_f32_32x32x16_bf16 v[66:81], v[154:157], v[102:105], v[66:81]
	v_mfma_f32_32x32x16_bf16 v[82:97], v[158:161], v[106:109], v[82:97]
	v_mfma_f32_32x32x16_bf16 v[66:81], v[162:165], v[106:109], v[66:81]
	v_mfma_f32_32x32x16_bf16 v[82:97], v[166:169], v[110:113], v[82:97]
	v_mfma_f32_32x32x16_bf16 v[66:81], v[170:173], v[110:113], v[66:81]
	s_and_b64 vcc, exec, s[2:3]
	s_cbranch_vccnz .Lm2a_w0
	s_waitcnt vmcnt(4)
	s_branch .Lm2a_w1

; __device__ __forceinline__ unsigned cvtpk(float lo, float hi) { unsigned r; asm("v_cvt_pk_bf16_f32 %0, %1, %2" : "=v"(r) : "v"(lo), "v"(hi)); return r; }
; __device__ __forceinline__ float max_x32(float v) { const unsigned u = __float_as_uint(v); auto r = __builtin_amdgcn_permlane32_swap(u, u, false, false); return fmaxf(__uint_as_float(r[0]), __uint_as_float(r[1])); }
; template <bool MASKED>
; __device__ __forceinline__ void softmax_tile(f32x16& s0, f32x16& s1, float& m, float& l, float& alpha, unsigned mlo, unsigned mhi, bf16x8 (&pk)[4]) {
;     ...
;     float mx = fmaxf(s0[0], s1[0]);
; #pragma unroll
;     for (int r = 1; r < 16; ++r) mx = fmaxf(mx, fmaxf(s0[r], s1[r]));
;     mx = max_x32(mx);
;     const float mn = fmaxf(m, mx);
;     alpha = __builtin_amdgcn_exp2f(m - mn); m = mn;
;     float sum = 0.f;
; #pragma unroll
;     for (int r = 0; r < 16; ++r) {
;         float p0 = __builtin_amdgcn_exp2f(s0[r] - mn), p1 = __builtin_amdgcn_exp2f(s1[r] - mn);
;         if (MASKED) { if (s0[r] <= -1e29f) p0 = 0.f; if (s1[r] <= -1e29f) p1 = 0.f; }
;         s0[r] = p0; s1[r] = p1; sum += p0 + p1;
;     }
;     l = l * alpha + sum;
; #pragma unroll
;     for (int k2 = 0; k2 < 2; ++k2) {
;         u32x4 a, b;
;         a.x = cvtpk(s0[8 * k2 + 0], s0[8 * k2 + 1]); a.y = cvtpk(s0[8 * k2 + 2], s0[8 * k2 + 3]); a.z = cvtpk(s0[8 * k2 + 4], s0[8 * k2 + 5]); a.w = cvtpk(s0[8 * k2 + 6], s0[8 * k2 + 7]);
;         b.x = cvtpk(s1[8 * k2 + 0], s1[8 * k2 + 1]); b.y = cvtpk(s1[8 * k2 + 2], s1[8 * k2 + 3]); b.z = cvtpk(s1[8 * k2 + 4], s1[8 * k2 + 5]); b.w = cvtpk(s1[8 * k2 + 6], s1[8 * k2 + 7]);
;         pk[k2] = __builtin_bit_cast(bf16x8, a); pk[2 + k2] = __builtin_bit_cast(bf16x8, b);
;     }
; }
.Lm2a_w1:
	s_barrier
	s_nop 11
	v_max_f32_e32 v0, v67, v67
	v_max_f32_e32 v146, v83, v83
	v_max_f32_e32 v0, v146, v0
	v_max_f32_e32 v146, v68, v68
	v_max_f32_e32 v149, v84, v84
	v_max_f32_e32 v146, v149, v146
	v_max_f32_e32 v149, v69, v69
	v_max_f32_e32 v150, v85, v85
	v_max3_f32 v0, v82, v66, v0
	v_max_f32_e32 v149, v150, v149
	v_max3_f32 v0, v0, v146, v149
	v_max_f32_e32 v146, v70, v70
	v_max_f32_e32 v149, v86, v86
	v_max_f32_e32 v146, v149, v146
	v_max_f32_e32 v149, v71, v71
	v_max_f32_e32 v150, v87, v87
	v_max_f32_e32 v149, v150, v149
	v_max3_f32 v0, v0, v146, v149
	v_max_f32_e32 v146, v72, v72
	v_max_f32_e32 v149, v88, v88
	v_max_f32_e32 v146, v149, v146
	v_max_f32_e32 v149, v73, v73
	v_max_f32_e32 v150, v89, v89
	v_max_f32_e32 v149, v150, v149
	v_max3_f32 v0, v0, v146, v149
	v_max_f32_e32 v146, v74, v74
	v_max_f32_e32 v149, v90, v90
	v_max_f32_e32 v146, v149, v146
	v_max_f32_e32 v149, v75, v75
	v_max_f32_e32 v150, v91, v91
	v_max_f32_e32 v149, v150, v149
	v_max3_f32 v0, v0, v146, v149
	v_max_f32_e32 v146, v76, v76
	v_max_f32_e32 v149, v92, v92
	v_max_f32_e32 v146, v149, v146
	v_max_f32_e32 v149, v77, v77
	v_max_f32_e32 v150, v93, v93
	v_max_f32_e32 v149, v150, v149
	v_max3_f32 v0, v0, v146, v149
	v_max_f32_e32 v146, v78, v78
	v_max_f32_e32 v149, v94, v94
	v_max_f32_e32 v146, v149, v146
	v_max_f32_e32 v149, v79, v79
	v_max_f32_e32 v150, v95, v95
	v_max_f32_e32 v149, v150, v149
	v_max3_f32 v0, v0, v146, v149
	v_max_f32_e32 v146, v80, v80
	v_max_f32_e32 v149, v96, v96
	v_max_f32_e32 v146, v149, v146
	v_max_f32_e32 v149, v81, v81
	v_max_f32_e32 v150, v97, v97
	v_max_f32_e32 v149, v150, v149
	v_max3_f32 v0, v0, v146, v149
	v_mov_b32_e32 v146, v0
	s_nop 1
	v_permlane32_swap_b32_e32 v0, v146
	v_max3_f32 v146, v148, v0, v146
	v_sub_f32_e32 v66, v66, v146
	v_sub_f32_e32 v0, v148, v146
	v_exp_f32_e32 v148, v66
	v_sub_f32_e32 v66, v83, v146
	v_exp_f32_e32 v83, v66
	v_sub_f32_e32 v66, v67, v146
	v_exp_f32_e32 v149, v66
	v_sub_f32_e32 v66, v84, v146
	v_exp_f32_e32 v84, v66
	v_sub_f32_e32 v66, v68, v146
	v_exp_f32_e32 v150, v66
	v_sub_f32_e32 v66, v85, v146
	v_exp_f32_e32 v85, v66
	v_sub_f32_e32 v66, v69, v146
	v_exp_f32_e32 v151, v66
	v_sub_f32_e32 v66, v86, v146
	v_exp_f32_e32 v86, v66
	v_sub_f32_e32 v66, v70, v146
	v_exp_f32_e32 v152, v66
	v_sub_f32_e32 v66, v87, v146
	v_exp_f32_e32 v87, v66
	v_sub_f32_e32 v66, v71, v146
	v_exp_f32_e32 v153, v66
	v_sub_f32_e32 v66, v88, v146
	v_exp_f32_e32 v88, v66
	v_sub_f32_e32 v66, v72, v146
	v_exp_f32_e32 v154, v66
	v_sub_f32_e32 v66, v89, v146
	v_exp_f32_e32 v89, v66
	v_sub_f32_e32 v66, v73, v146
	v_exp_f32_e32 v155, v66
	v_sub_f32_e32 v66, v90, v146
	v_exp_f32_e32 v90, v66
	v_sub_f32_e32 v66, v74, v146
	v_exp_f32_e32 v156, v66
	v_sub_f32_e32 v66, v91, v146
	v_exp_f32_e32 v91, v66
	v_sub_f32_e32 v66, v75, v146
	v_exp_f32_e32 v157, v66
	v_sub_f32_e32 v66, v92, v146
	v_exp_f32_e32 v92, v66
	v_sub_f32_e32 v66, v76, v146
	v_exp_f32_e32 v158, v66
	v_sub_f32_e32 v66, v93, v146
	v_exp_f32_e32 v93, v66
	v_sub_f32_e32 v66, v77, v146
	v_exp_f32_e32 v159, v66
	v_sub_f32_e32 v66, v94, v146
	v_exp_f32_e32 v94, v66
	v_sub_f32_e32 v66, v78, v146
	v_exp_f32_e32 v176, v66
	v_sub_f32_e32 v66, v95, v146
	v_exp_f32_e32 v95, v66
	v_sub_f32_e32 v66, v79, v146
	v_exp_f32_e32 v177, v66
	v_sub_f32_e32 v66, v96, v146
	v_exp_f32_e32 v96, v66
	v_sub_f32_e32 v66, v80, v146
	v_exp_f32_e32 v178, v66
	v_sub_f32_e32 v66, v97, v146
	v_exp_f32_e32 v0, v0
	v_sub_f32_e32 v82, v82, v146
	v_exp_f32_e32 v97, v66
	v_sub_f32_e32 v66, v81, v146
	v_exp_f32_e32 v82, v82
	v_exp_f32_e32 v179, v66
	v_cmp_neq_f32_e32 vcc, 1.0, v0
	v_cvt_pk_bf16_f32 v74, v82, v83
	v_cvt_pk_bf16_f32 v75, v84, v85
	v_cvt_pk_bf16_f32 v76, v86, v87
	v_cvt_pk_bf16_f32 v77, v88, v89
	v_cvt_pk_bf16_f32 v66, v148, v149
	v_cvt_pk_bf16_f32 v67, v150, v151
	v_cvt_pk_bf16_f32 v68, v152, v153
	v_cvt_pk_bf16_f32 v69, v154, v155
	v_cvt_pk_bf16_f32 v78, v90, v91
	v_cvt_pk_bf16_f32 v79, v92, v93
	v_cvt_pk_bf16_f32 v80, v94, v95
	v_cvt_pk_bf16_f32 v81, v96, v97
	v_cvt_pk_bf16_f32 v70, v156, v157
	v_cvt_pk_bf16_f32 v71, v158, v159
	v_cvt_pk_bf16_f32 v72, v176, v177
	v_cvt_pk_bf16_f32 v73, v178, v179
	s_cbranch_vccz .LBB0_629
	v_pk_mul_f32 v[64:65], v[64:65], v[0:1] op_sel_hi:[1,0]
	v_pk_mul_f32 v[62:63], v[62:63], v[0:1] op_sel_hi:[1,0]
	v_pk_mul_f32 v[60:61], v[60:61], v[0:1] op_sel_hi:[1,0]
	v_pk_mul_f32 v[58:59], v[58:59], v[0:1] op_sel_hi:[1,0]
	v_pk_mul_f32 v[56:57], v[56:57], v[0:1] op_sel_hi:[1,0]
	v_pk_mul_f32 v[54:55], v[54:55], v[0:1] op_sel_hi:[1,0]
	v_pk_mul_f32 v[52:53], v[52:53], v[0:1] op_sel_hi:[1,0]
	v_pk_mul_f32 v[50:51], v[50:51], v[0:1] op_sel_hi:[1,0]
	v_pk_mul_f32 v[48:49], v[48:49], v[0:1] op_sel_hi:[1,0]
	v_pk_mul_f32 v[46:47], v[46:47], v[0:1] op_sel_hi:[1,0]
	v_pk_mul_f32 v[44:45], v[44:45], v[0:1] op_sel_hi:[1,0]
	v_pk_mul_f32 v[42:43], v[42:43], v[0:1] op_sel_hi:[1,0]
	v_pk_mul_f32 v[40:41], v[40:41], v[0:1] op_sel_hi:[1,0]
	v_pk_mul_f32 v[38:39], v[38:39], v[0:1] op_sel_hi:[1,0]
	v_pk_mul_f32 v[36:37], v[36:37], v[0:1] op_sel_hi:[1,0]
	v_pk_mul_f32 v[34:35], v[34:35], v[0:1] op_sel_hi:[1,0]
	v_pk_mul_f32 v[32:33], v[32:33], v[0:1] op_sel_hi:[1,0]
	v_pk_mul_f32 v[30:31], v[30:31], v[0:1] op_sel_hi:[1,0]
	v_pk_mul_f32 v[28:29], v[28:29], v[0:1] op_sel_hi:[1,0]
	v_pk_mul_f32 v[26:27], v[26:27], v[0:1] op_sel_hi:[1,0]
	v_pk_mul_f32 v[24:25], v[24:25], v[0:1] op_sel_hi:[1,0]
	v_pk_mul_f32 v[22:23], v[22:23], v[0:1] op_sel_hi:[1,0]
	v_pk_mul_f32 v[20:21], v[20:21], v[0:1] op_sel_hi:[1,0]
	v_pk_mul_f32 v[18:19], v[18:19], v[0:1] op_sel_hi:[1,0]
	v_pk_mul_f32 v[16:17], v[16:17], v[0:1] op_sel_hi:[1,0]
	v_pk_mul_f32 v[14:15], v[14:15], v[0:1] op_sel_hi:[1,0]
	v_pk_mul_f32 v[12:13], v[12:13], v[0:1] op_sel_hi:[1,0]
	v_pk_mul_f32 v[10:11], v[10:11], v[0:1] op_sel_hi:[1,0]
	v_pk_mul_f32 v[8:9], v[8:9], v[0:1] op_sel_hi:[1,0]
	v_pk_mul_f32 v[6:7], v[6:7], v[0:1] op_sel_hi:[1,0]
	v_pk_mul_f32 v[4:5], v[4:5], v[0:1] op_sel_hi:[1,0]
	v_pk_mul_f32 v[2:3], v[2:3], v[0:1] op_sel_hi:[1,0]
.LBB0_629:
	v_add_f32_e32 v82, v82, v148
	v_add_f32_e32 v82, 0, v82
	v_add_f32_e32 v83, v83, v149
	v_add_f32_e32 v82, v83, v82
	v_add_f32_e32 v83, v84, v150
	v_add_f32_e32 v82, v83, v82
	v_add_f32_e32 v83, v85, v151
	v_add_f32_e32 v82, v83, v82
	v_add_f32_e32 v83, v86, v152
	v_add_f32_e32 v82, v83, v82
	v_add_f32_e32 v83, v87, v153
	v_add_f32_e32 v82, v83, v82
	v_add_f32_e32 v83, v88, v154
	v_add_f32_e32 v82, v83, v82
	v_add_f32_e32 v83, v89, v155
	v_add_f32_e32 v82, v83, v82
	v_add_f32_e32 v83, v90, v156
	v_add_f32_e32 v82, v83, v82
	v_add_f32_e32 v83, v91, v157
	v_add_f32_e32 v82, v83, v82
	v_add_f32_e32 v83, v92, v158
	v_add_f32_e32 v82, v83, v82
	v_add_f32_e32 v83, v93, v159
	v_add_f32_e32 v82, v83, v82
	v_add_f32_e32 v83, v94, v176
	v_add_f32_e32 v82, v83, v82
	v_add_f32_e32 v83, v95, v177
	v_add_f32_e32 v82, v83, v82
	v_add_f32_e32 v83, v96, v178
	v_add_f32_e32 v82, v83, v82
	v_add_f32_e32 v83, v97, v179
	v_add_f32_e32 v164, v83, v82
	v_fmac_f32_e32 v164, v147, v0
	s_barrier
	s_and_b64 vcc, exec, s[2:3]
	s_cbranch_vccnz .Lm2a_noV
	s_mul_i32 s100, s16, 0xa000
	v_lshl_add_u64 v[82:83], v[118:119], 0, s[4:5]
	s_add_i32 s100, s9, s100
	v_lshl_add_u64 v[82:83], v[82:83], 0, s[36:37]
	s_add_i32 m0, s100, 0x4000
	v_lshl_add_u64 v[84:85], v[116:117], 0, s[4:5]
	global_load_lds_dwordx4 v[82:83], off
	v_lshl_add_u64 v[84:85], v[84:85], 0, s[36:37]
	s_add_i32 m0, s100, 0x4400
	s_nop 0
	global_load_lds_dwordx4 v[84:85], off
.Lm2a_noV:
	v_add_u32_e32 v0, s26, v125
	v_add_u32_e32 v147, v0, v130
	v_add_u32_e32 v165, v0, v132
	v_add_u32_e32 v166, v0, v134
	v_add_u32_e32 v167, v0, v135
	v_add_u32_e32 v168, v0, v136
	v_add_u32_e32 v169, v0, v137
	v_add_u32_e32 v170, v0, v138
	v_add_u32_e32 v0, v0, v139
	v_add_u32_e32 v82, v147, v131
	v_add_u32_e32 v84, v165, v133
	v_add_u32_e32 v86, v166, v131
	v_add_u32_e32 v88, v167, v133
	v_add_u32_e32 v90, v168, v131
	v_add_u32_e32 v92, v169, v133
	v_add_u32_e32 v94, v170, v131
	v_add_u32_e32 v96, v0, v133
	v_add_u32_e32 v148, v147, v140
	v_add_u32_e32 v150, v165, v141
	v_add_u32_e32 v152, v166, v140
	v_add_u32_e32 v154, v167, v141
	v_add_u32_e32 v156, v168, v140
	v_add_u32_e32 v158, v169, v141
	v_add_u32_e32 v160, v170, v140
	v_add_u32_e32 v162, v0, v141
	ds_read_b64_tr_b16 v[82:83], v82
	ds_read_b64_tr_b16 v[84:85], v84
	ds_read_b64_tr_b16 v[86:87], v86
	ds_read_b64_tr_b16 v[88:89], v88
	ds_read_b64_tr_b16 v[90:91], v90
	ds_read_b64_tr_b16 v[92:93], v92
	ds_read_b64_tr_b16 v[94:95], v94
	ds_read_b64_tr_b16 v[96:97], v96
	ds_read_b64_tr_b16 v[148:149], v148
	ds_read_b64_tr_b16 v[150:151], v150
	ds_read_b64_tr_b16 v[152:153], v152
	ds_read_b64_tr_b16 v[154:155], v154
	ds_read_b64_tr_b16 v[156:157], v156
	ds_read_b64_tr_b16 v[158:159], v158
	ds_read_b64_tr_b16 v[160:161], v160
	ds_read_b64_tr_b16 v[162:163], v162
	s_waitcnt lgkmcnt(0)
	s_nop 0
	v_mfma_f32_32x32x16_bf16 v[50:65], v[82:85], v[74:77], v[50:65]
	v_mfma_f32_32x32x16_bf16 v[34:49], v[148:151], v[74:77], v[34:49]
	v_mfma_f32_32x32x16_bf16 v[50:65], v[86:89], v[78:81], v[50:65]
	v_mfma_f32_32x32x16_bf16 v[34:49], v[152:155], v[78:81], v[34:49]
	v_mfma_f32_32x32x16_bf16 v[50:65], v[90:93], v[66:69], v[50:65]
	v_mfma_f32_32x32x16_bf16 v[34:49], v[156:159], v[66:69], v[34:49]
	v_mfma_f32_32x32x16_bf16 v[50:65], v[94:97], v[70:73], v[50:65]
	v_mfma_f32_32x32x16_bf16 v[34:49], v[160:163], v[70:73], v[34:49]
	v_add_u32_e32 v82, v147, v142
	v_add_u32_e32 v84, v165, v143
	v_add_u32_e32 v86, v166, v142
	v_add_u32_e32 v88, v167, v143
	v_add_u32_e32 v90, v168, v142
	v_add_u32_e32 v92, v169, v143
	v_add_u32_e32 v94, v170, v142
	v_add_u32_e32 v96, v0, v143
	v_add_u32_e32 v147, v147, v144
	ds_read_b64_tr_b16 v[82:83], v82
	ds_read_b64_tr_b16 v[84:85], v84
	ds_read_b64_tr_b16 v[86:87], v86
	ds_read_b64_tr_b16 v[88:89], v88
	ds_read_b64_tr_b16 v[90:91], v90
	ds_read_b64_tr_b16 v[92:93], v92
	ds_read_b64_tr_b16 v[94:95], v94
	ds_read_b64_tr_b16 v[96:97], v96
	ds_read_b64_tr_b16 v[148:149], v147
	v_add_u32_e32 v147, v165, v145
	ds_read_b64_tr_b16 v[150:151], v147
	v_add_u32_e32 v147, v166, v144
	ds_read_b64_tr_b16 v[152:153], v147
	v_add_u32_e32 v147, v167, v145
	ds_read_b64_tr_b16 v[154:155], v147
	v_add_u32_e32 v147, v168, v144
	ds_read_b64_tr_b16 v[156:157], v147
	v_add_u32_e32 v147, v169, v145
	ds_read_b64_tr_b16 v[158:159], v147
	v_add_u32_e32 v147, v170, v144
	ds_read_b64_tr_b16 v[160:161], v147
	v_add_u32_e32 v0, v0, v145
	ds_read_b64_tr_b16 v[162:163], v0
	s_waitcnt lgkmcnt(0)
	v_mfma_f32_32x32x16_bf16 v[18:33], v[82:85], v[74:77], v[18:33]
	v_mfma_f32_32x32x16_bf16 v[2:17], v[148:151], v[74:77], v[2:17]
	v_mfma_f32_32x32x16_bf16 v[18:33], v[86:89], v[78:81], v[18:33]
	v_mfma_f32_32x32x16_bf16 v[2:17], v[152:155], v[78:81], v[2:17]
	v_mfma_f32_32x32x16_bf16 v[18:33], v[90:93], v[66:69], v[18:33]
	v_mfma_f32_32x32x16_bf16 v[2:17], v[156:159], v[66:69], v[2:17]
	v_mfma_f32_32x32x16_bf16 v[18:33], v[94:97], v[70:73], v[18:33]
	v_mfma_f32_32x32x16_bf16 v[2:17], v[160:163], v[70:73], v[2:17]
	v_mov_b32_e32 v147, v164
	s_andn2_b64 vcc, exec, s[2:3]
	s_mov_b64 s[2:3], -1
	s_cbranch_vccz .LBB0_631
	s_branch .LBB0_632
.LBB0_630:
	v_mov_b32_e32 v146, v148
	s_and_b64 vcc, exec, s[2:3]
	s_cbranch_vccnz .Lm2s_w0
	s_waitcnt vmcnt(4)
	s_branch .Lm2s_w1

; #define WAIT_TILE(all_) do { if (all_) asm volatile("s_waitcnt vmcnt(0) lgkmcnt(0)" ::: "memory"); \
;         else if constexpr (MODE == 0) asm volatile("s_waitcnt vmcnt(5) lgkmcnt(0)" ::: "memory"); else asm volatile("s_waitcnt vmcnt(4) lgkmcnt(0)" ::: "memory"); \
;         __builtin_amdgcn_s_barrier(); asm volatile("" ::: "memory"); } while (0)
; template <int MODE>
; __device__ __forceinline__ void attn_unit(LAS char* lds, const AttnPtrs& A, int b, int qb) {
;     ...
;         const bool more2 = (t + 2 < NT);
;         if (more2) STAGE(t + 2, st_nn);
;         if (t <= cw) {
;             const lptr sb = (lptr)(lds + st_cur * ST_BYTES);
;             f32x16 s0 = f32x16{}, s1 = f32x16{};
;             QK_PASS(NQ);
;             if constexpr (MODE == 1) softmax_tile<true>(s0, s1, m1, l1, a1, mlo, mhi, pk); else softmax_tile<false>(s0, s1, m1, l1, a1, 0, 0, pk);
;             PV_PASS(sb);
;         }
;         WAIT_TILE(!more2);
.Lm2s_w1:
	s_barrier
	s_barrier
	s_and_b64 vcc, exec, s[2:3]
	s_cbranch_vccnz .Lm2s_noV
	s_mul_i32 s100, s16, 0xa000
	v_lshl_add_u64 v[82:83], v[118:119], 0, s[4:5]
	s_add_i32 s100, s9, s100
	v_lshl_add_u64 v[82:83], v[82:83], 0, s[36:37]
	s_add_i32 m0, s100, 0x4000
	v_lshl_add_u64 v[84:85], v[116:117], 0, s[4:5]
	global_load_lds_dwordx4 v[82:83], off
	v_lshl_add_u64 v[84:85], v[84:85], 0, s[36:37]
	s_add_i32 m0, s100, 0x4400
	s_nop 0
	global_load_lds_dwordx4 v[84:85], off
.Lm2s_noV:
	s_andn2_b64 vcc, exec, s[2:3]
	s_mov_b64 s[2:3], -1
	s_cbranch_vccnz .LBB0_632

; #define LAS __attribute__((address_space(3)))
; __device__ __forceinline__ float sum_x32(float v) { const unsigned u = __float_as_uint(v); auto r = __builtin_amdgcn_permlane32_swap(u, u, false, false); return __uint_as_float(r[0]) + __uint_as_float(r[1]); }
; #define WAIT_TILE(all_) do { if (all_) asm volatile("s_waitcnt vmcnt(0) lgkmcnt(0)" ::: "memory"); \
;         else if constexpr (MODE == 0) asm volatile("s_waitcnt vmcnt(5) lgkmcnt(0)" ::: "memory"); else asm volatile("s_waitcnt vmcnt(4) lgkmcnt(0)" ::: "memory"); \
;         __builtin_amdgcn_s_barrier(); asm volatile("" ::: "memory"); } while (0)
; template <int MODE>
; __device__ __forceinline__ void attn_unit(LAS char* lds, const AttnPtrs& A, int b, int qb) {
;     ...
;         WAIT_TILE(!more2);
;         st_cur = (st_cur == 2) ? 0 : st_cur + 1; st_nn = (st_nn == 2) ? 0 : st_nn + 1;
;     }
;     ...
;     l1 = sum_x32(l1); const float i1 = 1.0f / l1;
;     float rstd = 1.f;
;     if constexpr (MODE == 2) {
;         LAS float* xb = (LAS float*)lds + (wid >> 1) * 4096 + lane;
;         if (strm == 1) { const float i2 = A.lam * i1;
; #pragma unroll
;             for (int c = 0; c < 4; ++c)
; #pragma unroll
;                 for (int r = 0; r < 16; ++r) xb[(c * 16 + r) * 64] = o1[c][r] * i2; }
.LBB0_634:
	s_add_i32 s2, s17, 1
	s_cmp_lg_u32 s17, 2
	s_cselect_b32 s17, s2, 0
	s_add_i32 s2, s16, 1
	s_cmp_lg_u32 s16, 2
	s_cselect_b32 s16, s2, 0
	s_add_i32 s7, s7, 1
	v_lshl_add_u64 v[116:117], v[116:117], 0, s[60:61]
	s_cmp_eq_u32 s6, s7
	v_lshl_add_u64 v[118:119], v[118:119], 0, s[60:61]
	s_cbranch_scc0 .LBB0_624
	s_cmp_gt_u32 s23, 1
	s_cbranch_scc1 .Lm2_noY
	s_barrier
.Lm2_noY:
	s_barrier
	v_mov_b32_e32 v0, v147
	s_nop 1
	v_permlane32_swap_b32_e32 v147, v0
	v_add_f32_e32 v0, v147, v0
	v_div_scale_f32 v66, s[2:3], v0, v0, 1.0
	v_rcp_f32_e32 v67, v66
	s_lshl_b32 s2, s23, 14
	s_add_i32 s2, s2, 0
	s_cmp_eq_u32 s8, 0
	v_fma_f32 v68, -v66, v67, 1.0
	v_fmac_f32_e32 v67, v68, v67
	v_div_scale_f32 v68, vcc, 1.0, v0, 1.0
	v_mul_f32_e32 v69, v68, v67
	v_fma_f32 v70, -v66, v69, v68
	v_fmac_f32_e32 v69, v70, v67
	v_fma_f32 v66, -v66, v69, v68
	v_div_fmas_f32 v66, v66, v67, v69
	v_div_fixup_f32 v0, v66, v0, 1.0
	s_cselect_b64 s[6:7], -1, 0
	s_cmp_lg_u32 s8, 0
	v_lshl_add_u32 v66, v123, 2, s2
	s_cbranch_scc0 .LBB0_637
	v_mul_f32_e32 v67, v120, v0
	v_mul_f32_e32 v68, v50, v67
	v_mul_f32_e32 v69, v51, v67
	ds_write2st64_b32 v66, v68, v69 offset1:1
	v_mul_f32_e32 v68, v52, v67
	v_mul_f32_e32 v69, v53, v67
	ds_write2st64_b32 v66, v68, v69 offset0:2 offset1:3
	v_mul_f32_e32 v68, v54, v67
	v_mul_f32_e32 v69, v55, v67
	ds_write2st64_b32 v66, v68, v69 offset0:4 offset1:5
	v_mul_f32_e32 v68, v56, v67
	v_mul_f32_e32 v69, v57, v67
	ds_write2st64_b32 v66, v68, v69 offset0:6 offset1:7
	v_mul_f32_e32 v68, v58, v67
	v_mul_f32_e32 v69, v59, v67
	ds_write2st64_b32 v66, v68, v69 offset0:8 offset1:9
	v_mul_f32_e32 v68, v60, v67
	v_mul_f32_e32 v69, v61, v67
	ds_write2st64_b32 v66, v68, v69 offset0:10 offset1:11
	v_mul_f32_e32 v68, v62, v67
	v_mul_f32_e32 v69, v63, v67
	ds_write2st64_b32 v66, v68, v69 offset0:12 offset1:13
	v_mul_f32_e32 v68, v64, v67
	v_mul_f32_e32 v69, v65, v67
	ds_write2st64_b32 v66, v68, v69 offset0:14 offset1:15
	v_mul_f32_e32 v68, v34, v67
	v_mul_f32_e32 v69, v35, v67
	ds_write2st64_b32 v66, v68, v69 offset0:16 offset1:17
	v_mul_f32_e32 v68, v36, v67
	v_mul_f32_e32 v69, v37, v67
	ds_write2st64_b32 v66, v68, v69 offset0:18 offset1:19
	v_mul_f32_e32 v68, v38, v67
	v_mul_f32_e32 v69, v39, v67
	ds_write2st64_b32 v66, v68, v69 offset0:20 offset1:21
	v_mul_f32_e32 v68, v40, v67
	v_mul_f32_e32 v69, v41, v67
	ds_write2st64_b32 v66, v68, v69 offset0:22 offset1:23
	v_mul_f32_e32 v68, v42, v67
	v_mul_f32_e32 v69, v43, v67
	ds_write2st64_b32 v66, v68, v69 offset0:24 offset1:25
	v_mul_f32_e32 v68, v44, v67
	v_mul_f32_e32 v69, v45, v67
	ds_write2st64_b32 v66, v68, v69 offset0:26 offset1:27
	v_mul_f32_e32 v68, v46, v67
	v_mul_f32_e32 v69, v47, v67
	ds_write2st64_b32 v66, v68, v69 offset0:28 offset1:29
	v_mul_f32_e32 v68, v48, v67
	v_mul_f32_e32 v69, v49, v67
	ds_write2st64_b32 v66, v68, v69 offset0:30 offset1:31
	v_mul_f32_e32 v68, v18, v67
	v_mul_f32_e32 v69, v19, v67
	ds_write2st64_b32 v66, v68, v69 offset0:32 offset1:33
	v_mul_f32_e32 v68, v20, v67
	v_mul_f32_e32 v69, v21, v67
	ds_write2st64_b32 v66, v68, v69 offset0:34 offset1:35
	v_mul_f32_e32 v68, v22, v67
	v_mul_f32_e32 v69, v23, v67
	ds_write2st64_b32 v66, v68, v69 offset0:36 offset1:37
	v_mul_f32_e32 v68, v24, v67
	v_mul_f32_e32 v69, v25, v67
	ds_write2st64_b32 v66, v68, v69 offset0:38 offset1:39
	v_mul_f32_e32 v68, v26, v67
	v_mul_f32_e32 v69, v27, v67
	ds_write2st64_b32 v66, v68, v69 offset0:40 offset1:41
	v_mul_f32_e32 v68, v28, v67
	v_mul_f32_e32 v69, v29, v67
	ds_write2st64_b32 v66, v68, v69 offset0:42 offset1:43
	v_mul_f32_e32 v68, v30, v67
	v_mul_f32_e32 v69, v31, v67
	ds_write2st64_b32 v66, v68, v69 offset0:44 offset1:45
	v_mul_f32_e32 v68, v32, v67
	v_mul_f32_e32 v69, v33, v67
	ds_write2st64_b32 v66, v68, v69 offset0:46 offset1:47
	v_mul_f32_e32 v68, v2, v67
	v_mul_f32_e32 v69, v3, v67
	ds_write2st64_b32 v66, v68, v69 offset0:48 offset1:49
	v_mul_f32_e32 v68, v4, v67
	v_mul_f32_e32 v69, v5, v67
	ds_write2st64_b32 v66, v68, v69 offset0:50 offset1:51
	v_mul_f32_e32 v68, v6, v67
	v_mul_f32_e32 v69, v7, v67
	ds_write2st64_b32 v66, v68, v69 offset0:52 offset1:53
	v_mul_f32_e32 v68, v8, v67
	v_mul_f32_e32 v69, v9, v67
	ds_write2st64_b32 v66, v68, v69 offset0:54 offset1:55
	v_mul_f32_e32 v68, v10, v67
	v_mul_f32_e32 v69, v11, v67
	ds_write2st64_b32 v66, v68, v69 offset0:56 offset1:57
	v_mul_f32_e32 v68, v12, v67
	v_mul_f32_e32 v69, v13, v67
	ds_write2st64_b32 v66, v68, v69 offset0:58 offset1:59
	v_mul_f32_e32 v68, v14, v67
	v_mul_f32_e32 v69, v15, v67
	ds_write2st64_b32 v66, v68, v69 offset0:60 offset1:61
	v_mul_f32_e32 v68, v16, v67
	v_mul_f32_e32 v67, v17, v67
	ds_write2st64_b32 v66, v68, v67 offset0:62 offset1:63

; #define LAS __attribute__((address_space(3)))
; #define XBAR_MAKE() argp_t apb = (argp_t)__builtin_amdgcn_kernarg_segment_ptr(); asm volatile("" : "+s"(apb)); unsigned* barw = (unsigned*)(apb->ws + WS_CTRL) + CW_BAR
; #define GSYNC() do { XBAR_MAKE(); XcdBarrier xb_; xb_.bar = barw; xb_.x = xb_xcc_id(); xb_.st = (volatile LAS unsigned*)(uintptr_t)(LDS_MAIN + 16); for (int rs_ = 0; rs_ < REP_SYNC; ++rs_) xcd_barrier(xb_); } while (0)
; __global__ void __launch_bounds__(512, 2) hybrid_fwd(Args a_kernarg) {
;     cg::grid_group grid = cg::this_grid();
;     init_wave_table();
;     run_phase<0>(0);
;     grid.sync();
;     ...
;     { XBAR_MAKE(); (void)xcd_barrier_post(barw, (volatile LAS unsigned*)(uintptr_t)(LDS_MAIN + 16)); }
;     ...
;     for (int L = 0; L < DEPTH; ++L) {
;         run_phase<1>(L); GSYNC();
;         run_phase<2>(L); GSYNC();
;         run_phase<3>(L); GSYNC();
;         run_phase<4>(L); GSYNC();
;         run_phase<5>(L); GSYNC();
;     }
;     run_phase<6>(0);
; }
	.amdhsa_kernel _Z10hybrid_fwd4Args
		.amdhsa_group_segment_fixed_size 0
		.amdhsa_private_segment_fixed_size 0
		.amdhsa_kernarg_size 416
		.amdhsa_user_sgpr_count 2
		.amdhsa_user_sgpr_dispatch_ptr 0
		.amdhsa_user_sgpr_queue_ptr 0
		.amdhsa_user_sgpr_kernarg_segment_ptr 1
		.amdhsa_user_sgpr_dispatch_id 0
		.amdhsa_user_sgpr_kernarg_preload_length 0
		.amdhsa_user_sgpr_kernarg_preload_offset 0
		.amdhsa_user_sgpr_private_segment_size 0
		.amdhsa_uses_dynamic_stack 0
		.amdhsa_enable_private_segment 0
		.amdhsa_system_sgpr_workgroup_id_x 1
		.amdhsa_system_sgpr_workgroup_id_y 0
		.amdhsa_system_sgpr_workgroup_id_z 0
		.amdhsa_system_sgpr_workgroup_info 0
		.amdhsa_system_vgpr_workitem_id 2
		.amdhsa_next_free_vgpr 256
		.amdhsa_next_free_sgpr 102
		.amdhsa_accum_offset 256
		.amdhsa_reserve_vcc 1
		.amdhsa_float_round_mode_32 0
		.amdhsa_float_round_mode_16_64 0
		.amdhsa_float_denorm_mode_32 3
		.amdhsa_float_denorm_mode_16_64 3
		.amdhsa_dx10_clamp 1
		.amdhsa_ieee_mode 1
		.amdhsa_fp16_overflow 0
		.amdhsa_tg_split 0
		.amdhsa_exception_fp_ieee_invalid_op 0
		.amdhsa_exception_fp_denorm_src 0
		.amdhsa_exception_fp_ieee_div_zero 0
		.amdhsa_exception_fp_ieee_overflow 0
		.amdhsa_exception_fp_ieee_underflow 0
		.amdhsa_exception_fp_ieee_inexact 0
		.amdhsa_exception_int_div_zero 0
	.end_amdhsa_kernel

; __global__ void __launch_bounds__(512, 2) hybrid_fwd(Args a_kernarg) {
amdhsa.kernels:
  - .agpr_count:     0
    .args:
      - .offset:         0
        .size:           160
        .value_kind:     by_value
      - .offset:         160
        .size:           4
        .value_kind:     hidden_block_count_x
      - .offset:         164
        .size:           4
        .value_kind:     hidden_block_count_y
      - .offset:         168
        .size:           4
        .value_kind:     hidden_block_count_z
      - .offset:         172
        .size:           2
        .value_kind:     hidden_group_size_x
      - .offset:         174
        .size:           2
        .value_kind:     hidden_group_size_y
      - .offset:         176
        .size:           2
        .value_kind:     hidden_group_size_z
      - .offset:         178
        .size:           2
        .value_kind:     hidden_remainder_x
      - .offset:         180
        .size:           2
        .value_kind:     hidden_remainder_y
      - .offset:         182
        .size:           2
        .value_kind:     hidden_remainder_z
      - .offset:         200
        .size:           8
        .value_kind:     hidden_global_offset_x
      - .offset:         208
        .size:           8
        .value_kind:     hidden_global_offset_y
      - .offset:         216
        .size:           8
        .value_kind:     hidden_global_offset_z
      - .offset:         224
        .size:           2
        .value_kind:     hidden_grid_dims
      - .offset:         248
        .size:           8
        .value_kind:     hidden_multigrid_sync_arg
      - .offset:         280
        .size:           4
        .value_kind:     hidden_dynamic_lds_size
    .group_segment_fixed_size: 0
    .kernarg_segment_align: 8
    .kernarg_segment_size: 416
    .language:       OpenCL C
    .language_version:
      - 2
      - 0
    .max_flat_workgroup_size: 512
    .name:           _Z10hybrid_fwd4Args
    .private_segment_fixed_size: 0
    .sgpr_count:     108
    .sgpr_spill_count: 99
    .symbol:         _Z10hybrid_fwd4Args.kd
    .uniform_work_group_size: 1
    .uses_dynamic_stack: false
    .vgpr_count:     256
    .vgpr_spill_count: 0
    .wavefront_size: 64
